# v026 + P6 (out-projection + f32 residual) epilogue: residual-base loads in a rolling window of four row groups (requested ahead into scratch registers) instead of eight serialized load round trips per
# baseline (speedup 1.0000x reference)
; __device__ __forceinline__ unsigned cvt_pk_bf16(float lo, float hi) { const cvt_f32x2_t v = {lo, hi}; const cvt_bf16x2_t b = __builtin_convertvector(v, cvt_bf16x2_t); return __builtin_bit_cast(unsigned, b); }
;     __device__ __forceinline__ void operator()(const f32x4 (&acc)[2][2][4][2], const Unit& u, int wr, int wc, int fr, int fq) const {
;     ...
;             for (int m = 0; m < 4; ++m) { const int rowg = u.pm * BM + ai * HALF + wr * 64 + m * 16, row = rowg + fr; const size_t off = (size_t)row * 1024 + col0;
;                 u32x4 w[2]; float ss = 0.f;
; #pragma unroll
;                 for (int bj = 0; bj < 2; ++bj) { f32x4 b0, b1;
;                     if (BASE_F32) { const float* bp = (const float*)base + off + 32 * bj; b0 = *(const f32x4*)bp; b1 = *(const f32x4*)(bp + 4); }
;                     else { const u32x4 bb = *(const u32x4*)((const bf16_t*)base + off + 32 * bj);
;                         b0 = (f32x4){__uint_as_float(bb.x << 16), __uint_as_float(bb.x & 0xffff0000u), __uint_as_float(bb.y << 16), __uint_as_float(bb.y & 0xffff0000u)};
;                         b1 = (f32x4){__uint_as_float(bb.z << 16), __uint_as_float(bb.z & 0xffff0000u), __uint_as_float(bb.w << 16), __uint_as_float(bb.w & 0xffff0000u)}; }
;                     const f32x4 o0 = b0 + acc[ai][bj][m][0], o1 = b1 + acc[ai][bj][m][1];
;                     ss += ((o0[0] * o0[0] + o0[1] * o0[1]) + (o0[2] * o0[2] + o0[3] * o0[3])) + ((o1[0] * o1[0] + o1[1] * o1[1]) + (o1[2] * o1[2] + o1[3] * o1[3]));
;                     w[bj].x = cvt_pk_bf16(o0[0], o0[1]); w[bj].y = cvt_pk_bf16(o0[2], o0[3]); w[bj].z = cvt_pk_bf16(o1[0], o1[1]); w[bj].w = cvt_pk_bf16(o1[2], o1[3]); }
;                 ss += __shfl_xor(ss, 16); ss += __shfl_xor(ss, 32); if (fq == 0) slots[(size_t)row * 16 + u.pn * 4 + wc] = ss;
.LBB0_588:
	s_lshl_b32 s19, s48, 8
	s_add_i32 s19, s19, s56
	v_or_b32_e32 v148, s19, v150
	v_ashrrev_i32_e32 v149, 31, v148
	v_readlane_b32 s64, v239, 10
	v_lshl_or_b32 v146, s10, 8, v156
	v_lshlrev_b64 v[162:163], 12, v[148:149]
	v_readlane_b32 s65, v239, 11
	v_ashrrev_i32_e32 v147, 31, v146
	v_and_b32_e32 v178, 64, v160
	v_lshl_add_u64 v[162:163], s[64:65], 0, v[162:163]
	v_lshl_add_u64 v[174:175], v[146:147], 2, v[162:163]
	v_mov_b64_e32 v[234:235], v[174:175]
	s_mov_b32 s99, 0
	global_load_dwordx4 v[180:183], v[234:235], off
	global_load_dwordx4 v[184:187], v[234:235], off offset:16
	global_load_dwordx4 v[188:191], v[234:235], off offset:128
	global_load_dwordx4 v[192:195], v[234:235], off offset:144
	s_mov_b32 s98, 0x10000
	v_lshl_add_u64 v[232:233], v[234:235], 0, s[98:99]
	global_load_dwordx4 v[196:199], v[232:233], off
	global_load_dwordx4 v[200:203], v[232:233], off offset:16
	global_load_dwordx4 v[204:207], v[232:233], off offset:128
	global_load_dwordx4 v[208:211], v[232:233], off offset:144
	s_mov_b32 s98, 0x20000
	v_lshl_add_u64 v[232:233], v[234:235], 0, s[98:99]
	global_load_dwordx4 v[212:215], v[232:233], off
	global_load_dwordx4 v[216:219], v[232:233], off offset:16
	global_load_dwordx4 v[220:223], v[232:233], off offset:128
	global_load_dwordx4 v[224:227], v[232:233], off offset:144
	s_mov_b32 s98, 0x30000
	v_lshl_add_u64 v[232:233], v[234:235], 0, s[98:99]
	global_load_dwordx4 v[240:243], v[232:233], off
	global_load_dwordx4 v[244:247], v[232:233], off offset:16
	global_load_dwordx4 v[248:251], v[232:233], off offset:128
	global_load_dwordx4 v[252:255], v[232:233], off offset:144
	s_nop 0
	v_xor_b32_e32 v161, 16, v160
	v_add_u32_e32 v178, 64, v178
	v_cmp_lt_i32_e32 vcc, v161, v178
	s_lshl_b32 s0, s10, 2
	s_ashr_i32 s1, s0, 31
	v_cndmask_b32_e32 v161, v160, v161, vcc
	v_lshlrev_b32_e32 v161, 2, v161
	v_readlane_b32 s66, v239, 12
	v_readlane_b32 s67, v239, 13
	v_readlane_b32 s68, v239, 14
	v_readlane_b32 s69, v239, 15
	v_readlane_b32 s70, v239, 16
	v_readlane_b32 s71, v239, 17
	v_readlane_b32 s72, v239, 18
	v_readlane_b32 s73, v239, 19
	v_readlane_b32 s74, v239, 20
	v_readlane_b32 s75, v239, 21
	v_readlane_b32 s76, v239, 22
	v_readlane_b32 s77, v239, 23
	v_readlane_b32 s78, v239, 24
	v_readlane_b32 s79, v239, 25
	s_waitcnt vmcnt(12)
	v_mov_b64_e32 v[162:163], v[180:181]
	v_mov_b64_e32 v[164:165], v[182:183]
	v_mov_b64_e32 v[166:167], v[184:185]
	v_mov_b64_e32 v[168:169], v[186:187]
	v_mov_b64_e32 v[170:171], v[188:189]
	v_mov_b64_e32 v[172:173], v[190:191]
	v_mov_b64_e32 v[174:175], v[192:193]
	v_mov_b64_e32 v[176:177], v[194:195]
	s_mov_b32 s98, 0x80000
	v_lshl_add_u64 v[232:233], v[234:235], 0, s[98:99]
	global_load_dwordx4 v[180:183], v[232:233], off
	global_load_dwordx4 v[184:187], v[232:233], off offset:16
	global_load_dwordx4 v[188:191], v[232:233], off offset:128
	global_load_dwordx4 v[192:195], v[232:233], off offset:144
	v_pk_add_f32 v[126:127], v[126:127], v[164:165]
	v_pk_add_f32 v[124:125], v[124:125], v[162:163]
	v_pk_add_f32 v[122:123], v[122:123], v[168:169]
	v_pk_add_f32 v[120:121], v[120:121], v[166:167]
	v_pk_add_f32 v[118:119], v[118:119], v[172:173]
	v_pk_add_f32 v[116:117], v[116:117], v[170:171]
	v_pk_add_f32 v[114:115], v[114:115], v[176:177]
	v_pk_add_f32 v[112:113], v[112:113], v[174:175]
	v_mul_f32_e32 v162, v125, v125
	v_mul_f32_e32 v163, v127, v127
	v_mul_f32_e32 v164, v121, v121
	v_mul_f32_e32 v165, v123, v123
	v_mul_f32_e32 v166, v117, v117
	v_mul_f32_e32 v167, v119, v119
	v_mul_f32_e32 v168, v113, v113
	v_mul_f32_e32 v169, v115, v115
	v_fmac_f32_e32 v162, v124, v124
	v_fmac_f32_e32 v163, v126, v126
	v_fmac_f32_e32 v164, v120, v120
	v_fmac_f32_e32 v165, v122, v122
	v_fmac_f32_e32 v166, v116, v116
	v_fmac_f32_e32 v167, v118, v118
	v_fmac_f32_e32 v168, v112, v112
	v_fmac_f32_e32 v169, v114, v114
	v_add_f32_e32 v162, v162, v163
	v_add_f32_e32 v163, v164, v165
	v_add_f32_e32 v164, v166, v167
	v_add_f32_e32 v165, v168, v169
	v_add_f32_e32 v162, v162, v163
	v_add_f32_e32 v163, v164, v165
	v_add_f32_e32 v163, v162, v163
	ds_bpermute_b32 v164, v161, v163
	v_xor_b32_e32 v162, 32, v160
	v_cmp_lt_i32_e32 vcc, v162, v178
	s_waitcnt lgkmcnt(0)
	v_add_f32_e32 v163, v163, v164
	v_cndmask_b32_e32 v162, v160, v162, vcc
	v_lshlrev_b32_e32 v162, 2, v162
	ds_bpermute_b32 v164, v162, v163
	s_and_saveexec_b64 s[20:21], s[2:3]
	v_readlane_b32 s30, v239, 49
	v_readlane_b32 s31, v239, 50
	s_cbranch_execz .LBB0_590
	v_lshlrev_b64 v[148:149], 6, v[148:149]
	v_lshl_add_u64 v[148:149], s[82:83], 0, v[148:149]
	v_lshl_add_u64 v[148:149], s[0:1], 2, v[148:149]
	s_lshl_b32 s10, s55, 2
	v_lshl_add_u64 v[148:149], v[148:149], 0, s[10:11]
	s_waitcnt lgkmcnt(0)
	v_add_f32_e32 v163, v163, v164
	global_store_dword v[148:149], v163, off
; __device__ __forceinline__ unsigned cvt_pk_bf16(float lo, float hi) { const cvt_f32x2_t v = {lo, hi}; const cvt_bf16x2_t b = __builtin_convertvector(v, cvt_bf16x2_t); return __builtin_bit_cast(unsigned, b); }
; __device__ __forceinline__ void wide_store(bf16_t* O, int ldc, int rowg  , int col0  , int fr, u32x4 w0, u32x4 w1) {
;     const bool lo = fr < 8;
;     u32x4 snd = lo ? w1 : w0, rcv;
;     rcv.x = swap8(snd.x); rcv.y = swap8(snd.y); rcv.z = swap8(snd.z); rcv.w = swap8(snd.w);
;     const u32x4 first = lo ? w0 : rcv, second = lo ? rcv : w1;
;     bf16_t* p = O + (size_t)(rowg + (fr & 7)) * ldc + col0 + (lo ? 0 : 32);
;     __builtin_nontemporal_store(first, (u32x4*)p); __builtin_nontemporal_store(second, (u32x4*)(p + (size_t)8 * ldc));
; }
;     __device__ __forceinline__ void operator()(const f32x4 (&acc)[2][2][4][2], const Unit& u, int wr, int wc, int fr, int fq) const {
;     ...
;             for (int m = 0; m < 4; ++m) { const int rowg = u.pm * BM + ai * HALF + wr * 64 + m * 16, row = rowg + fr; const size_t off = (size_t)row * 1024 + col0;
;                 u32x4 w[2]; float ss = 0.f;
; #pragma unroll
;                 for (int bj = 0; bj < 2; ++bj) { f32x4 b0, b1;
;                     if (BASE_F32) { const float* bp = (const float*)base + off + 32 * bj; b0 = *(const f32x4*)bp; b1 = *(const f32x4*)(bp + 4); }
;                     else { const u32x4 bb = *(const u32x4*)((const bf16_t*)base + off + 32 * bj);
;                         b0 = (f32x4){__uint_as_float(bb.x << 16), __uint_as_float(bb.x & 0xffff0000u), __uint_as_float(bb.y << 16), __uint_as_float(bb.y & 0xffff0000u)};
;                         b1 = (f32x4){__uint_as_float(bb.z << 16), __uint_as_float(bb.z & 0xffff0000u), __uint_as_float(bb.w << 16), __uint_as_float(bb.w & 0xffff0000u)}; }
;                     const f32x4 o0 = b0 + acc[ai][bj][m][0], o1 = b1 + acc[ai][bj][m][1];
;                     ss += ((o0[0] * o0[0] + o0[1] * o0[1]) + (o0[2] * o0[2] + o0[3] * o0[3])) + ((o1[0] * o1[0] + o1[1] * o1[1]) + (o1[2] * o1[2] + o1[3] * o1[3]));
;                     w[bj].x = cvt_pk_bf16(o0[0], o0[1]); w[bj].y = cvt_pk_bf16(o0[2], o0[3]); w[bj].z = cvt_pk_bf16(o1[0], o1[1]); w[bj].w = cvt_pk_bf16(o1[2], o1[3]); }
;                 ss += __shfl_xor(ss, 16); ss += __shfl_xor(ss, 32); if (fq == 0) slots[(size_t)row * 16 + u.pn * 4 + wc] = ss;
.LBB0_590:
	s_or_b64 exec, exec, s[20:21]
	v_cvt_pk_bf16_f32 v120, v120, v121
	v_cvt_pk_bf16_f32 v116, v116, v117
	v_cvt_pk_bf16_f32 v117, v118, v119
	v_cvt_pk_bf16_f32 v118, v112, v113
	v_cvt_pk_bf16_f32 v124, v124, v125
	v_cvt_pk_bf16_f32 v125, v126, v127
	v_cvt_pk_bf16_f32 v121, v122, v123
	v_cvt_pk_bf16_f32 v119, v114, v115
	v_cndmask_b32_e64 v113, v120, v118, s[4:5]
	v_mov_b32_e32 v126, v137
	v_cndmask_b32_e64 v112, v121, v119, s[4:5]
	v_cndmask_b32_e64 v114, v125, v117, s[4:5]
	v_mov_b32_e32 v123, v137
	v_mov_b32_dpp v126, v113 row_ror:8 row_mask:0xf bank_mask:0xf
	v_mov_b32_e32 v127, v137
	v_cndmask_b32_e64 v115, v124, v116, s[4:5]
	v_mov_b32_e32 v122, v137
	v_mov_b32_dpp v123, v114 row_ror:8 row_mask:0xf bank_mask:0xf
	v_mov_b32_dpp v127, v112 row_ror:8 row_mask:0xf bank_mask:0xf
	v_cndmask_b32_e64 v114, v126, v120, s[4:5]
	v_or_b32_e32 v120, s19, v151
	v_mov_b32_dpp v122, v115 row_ror:8 row_mask:0xf bank_mask:0xf
	v_cndmask_b32_e64 v115, v127, v121, s[4:5]
	v_ashrrev_i32_e32 v121, 31, v120
	v_lshlrev_b64 v[120:121], 11, v[120:121]
	v_lshl_add_u64 v[120:121], s[30:31], 0, v[120:121]
	v_lshl_add_u64 v[120:121], v[146:147], 1, v[120:121]
	v_cndmask_b32_e64 v113, v123, v125, s[4:5]
	v_cndmask_b32_e64 v112, v122, v124, s[4:5]
	v_lshl_add_u64 v[120:121], v[120:121], 0, v[136:137]
	global_store_dwordx4 v[120:121], v[112:115], off nt
	v_cndmask_b32_e64 v119, v119, v127, s[4:5]
	v_cndmask_b32_e64 v118, v118, v126, s[4:5]
	v_add_co_u32_e32 v112, vcc, s52, v120
	v_cndmask_b32_e64 v117, v117, v123, s[4:5]
	v_cndmask_b32_e64 v116, v116, v122, s[4:5]
	v_addc_co_u32_e32 v113, vcc, 0, v121, vcc
	s_or_b32 s22, s19, 16
	global_store_dwordx4 v[112:113], v[116:119], off nt
	v_or_b32_e32 v112, s22, v150
	v_ashrrev_i32_e32 v113, 31, v112
	v_readlane_b32 s64, v239, 10
	v_lshlrev_b64 v[114:115], 12, v[112:113]
	v_readlane_b32 s65, v239, 11
	v_readlane_b32 s66, v239, 12
	v_readlane_b32 s67, v239, 13
	v_lshl_add_u64 v[114:115], s[64:65], 0, v[114:115]
	v_lshl_add_u64 v[126:127], v[146:147], 2, v[114:115]
	s_waitcnt lgkmcnt(0)
	v_readlane_b32 s68, v239, 14
	v_readlane_b32 s69, v239, 15
	v_readlane_b32 s70, v239, 16
	v_readlane_b32 s71, v239, 17
	v_readlane_b32 s72, v239, 18
	v_readlane_b32 s73, v239, 19
	v_readlane_b32 s74, v239, 20
	v_readlane_b32 s75, v239, 21
	v_readlane_b32 s76, v239, 22
	v_readlane_b32 s77, v239, 23
	v_readlane_b32 s78, v239, 24
	v_readlane_b32 s79, v239, 25
	s_waitcnt vmcnt(15)
	v_mov_b64_e32 v[114:115], v[196:197]
	v_mov_b64_e32 v[116:117], v[198:199]
	v_mov_b64_e32 v[118:119], v[200:201]
	v_mov_b64_e32 v[120:121], v[202:203]
	v_mov_b64_e32 v[122:123], v[204:205]
	v_mov_b64_e32 v[124:125], v[206:207]
	v_mov_b64_e32 v[164:165], v[208:209]
	v_mov_b64_e32 v[166:167], v[210:211]
	s_mov_b32 s98, 0x90000
	v_lshl_add_u64 v[232:233], v[234:235], 0, s[98:99]
	global_load_dwordx4 v[196:199], v[232:233], off
	global_load_dwordx4 v[200:203], v[232:233], off offset:16
	global_load_dwordx4 v[204:207], v[232:233], off offset:128
	global_load_dwordx4 v[208:211], v[232:233], off offset:144
	v_pk_add_f32 v[110:111], v[110:111], v[116:117]
	v_pk_add_f32 v[108:109], v[108:109], v[114:115]
	v_pk_add_f32 v[106:107], v[106:107], v[120:121]
	v_pk_add_f32 v[104:105], v[104:105], v[118:119]
	v_pk_add_f32 v[102:103], v[102:103], v[124:125]
	v_pk_add_f32 v[100:101], v[100:101], v[122:123]
	v_pk_add_f32 v[98:99], v[98:99], v[166:167]
	v_pk_add_f32 v[96:97], v[96:97], v[164:165]
	v_mul_f32_e32 v114, v109, v109
	v_mul_f32_e32 v115, v111, v111
	v_mul_f32_e32 v116, v105, v105
	v_mul_f32_e32 v117, v107, v107
	v_mul_f32_e32 v118, v101, v101
	v_mul_f32_e32 v119, v103, v103
	v_mul_f32_e32 v120, v97, v97
	v_mul_f32_e32 v121, v99, v99
	v_fmac_f32_e32 v114, v108, v108
	v_fmac_f32_e32 v115, v110, v110
	v_fmac_f32_e32 v116, v104, v104
	v_fmac_f32_e32 v117, v106, v106
	v_fmac_f32_e32 v118, v100, v100
	v_fmac_f32_e32 v119, v102, v102
	v_fmac_f32_e32 v120, v96, v96
	v_fmac_f32_e32 v121, v98, v98
	v_add_f32_e32 v114, v114, v115
	v_add_f32_e32 v115, v116, v117
	v_add_f32_e32 v116, v118, v119
	v_add_f32_e32 v117, v120, v121
	v_add_f32_e32 v114, v114, v115
	v_add_f32_e32 v115, v116, v117
	v_add_f32_e32 v114, v114, v115
	ds_bpermute_b32 v115, v161, v114
	s_waitcnt lgkmcnt(0)
	v_add_f32_e32 v114, v114, v115
	ds_bpermute_b32 v115, v162, v114
	s_and_saveexec_b64 s[20:21], s[2:3]
	s_cbranch_execz .LBB0_592
	v_lshlrev_b64 v[112:113], 6, v[112:113]
	v_lshl_add_u64 v[112:113], s[82:83], 0, v[112:113]
	v_lshl_add_u64 v[112:113], s[0:1], 2, v[112:113]
	s_lshl_b32 s10, s55, 2
	v_lshl_add_u64 v[112:113], v[112:113], 0, s[10:11]
	s_waitcnt lgkmcnt(0)
	v_add_f32_e32 v114, v114, v115
	global_store_dword v[112:113], v114, off
; __device__ __forceinline__ unsigned cvt_pk_bf16(float lo, float hi) { const cvt_f32x2_t v = {lo, hi}; const cvt_bf16x2_t b = __builtin_convertvector(v, cvt_bf16x2_t); return __builtin_bit_cast(unsigned, b); }
; __device__ __forceinline__ void wide_store(bf16_t* O, int ldc, int rowg  , int col0  , int fr, u32x4 w0, u32x4 w1) {
;     const bool lo = fr < 8;
;     u32x4 snd = lo ? w1 : w0, rcv;
;     rcv.x = swap8(snd.x); rcv.y = swap8(snd.y); rcv.z = swap8(snd.z); rcv.w = swap8(snd.w);
;     const u32x4 first = lo ? w0 : rcv, second = lo ? rcv : w1;
;     bf16_t* p = O + (size_t)(rowg + (fr & 7)) * ldc + col0 + (lo ? 0 : 32);
;     __builtin_nontemporal_store(first, (u32x4*)p); __builtin_nontemporal_store(second, (u32x4*)(p + (size_t)8 * ldc));
; }
;     __device__ __forceinline__ void operator()(const f32x4 (&acc)[2][2][4][2], const Unit& u, int wr, int wc, int fr, int fq) const {
;     ...
;             for (int m = 0; m < 4; ++m) { const int rowg = u.pm * BM + ai * HALF + wr * 64 + m * 16, row = rowg + fr; const size_t off = (size_t)row * 1024 + col0;
;                 u32x4 w[2]; float ss = 0.f;
; #pragma unroll
;                 for (int bj = 0; bj < 2; ++bj) { f32x4 b0, b1;
;                     if (BASE_F32) { const float* bp = (const float*)base + off + 32 * bj; b0 = *(const f32x4*)bp; b1 = *(const f32x4*)(bp + 4); }
;                     else { const u32x4 bb = *(const u32x4*)((const bf16_t*)base + off + 32 * bj);
;                         b0 = (f32x4){__uint_as_float(bb.x << 16), __uint_as_float(bb.x & 0xffff0000u), __uint_as_float(bb.y << 16), __uint_as_float(bb.y & 0xffff0000u)};
;                         b1 = (f32x4){__uint_as_float(bb.z << 16), __uint_as_float(bb.z & 0xffff0000u), __uint_as_float(bb.w << 16), __uint_as_float(bb.w & 0xffff0000u)}; }
;                     const f32x4 o0 = b0 + acc[ai][bj][m][0], o1 = b1 + acc[ai][bj][m][1];
;                     ss += ((o0[0] * o0[0] + o0[1] * o0[1]) + (o0[2] * o0[2] + o0[3] * o0[3])) + ((o1[0] * o1[0] + o1[1] * o1[1]) + (o1[2] * o1[2] + o1[3] * o1[3]));
;                     w[bj].x = cvt_pk_bf16(o0[0], o0[1]); w[bj].y = cvt_pk_bf16(o0[2], o0[3]); w[bj].z = cvt_pk_bf16(o1[0], o1[1]); w[bj].w = cvt_pk_bf16(o1[2], o1[3]); }
;                 ss += __shfl_xor(ss, 16); ss += __shfl_xor(ss, 32); if (fq == 0) slots[(size_t)row * 16 + u.pn * 4 + wc] = ss;
.LBB0_592:
	s_or_b64 exec, exec, s[20:21]
	v_cvt_pk_bf16_f32 v104, v104, v105
	v_cvt_pk_bf16_f32 v100, v100, v101
	v_cvt_pk_bf16_f32 v101, v102, v103
	v_cvt_pk_bf16_f32 v102, v96, v97
	v_cvt_pk_bf16_f32 v108, v108, v109
	v_cvt_pk_bf16_f32 v109, v110, v111
	v_cvt_pk_bf16_f32 v105, v106, v107
	v_cvt_pk_bf16_f32 v103, v98, v99
	v_cndmask_b32_e64 v97, v104, v102, s[4:5]
	v_mov_b32_e32 v110, v137
	v_cndmask_b32_e64 v96, v105, v103, s[4:5]
	v_cndmask_b32_e64 v98, v109, v101, s[4:5]
	v_mov_b32_e32 v107, v137
	v_mov_b32_dpp v110, v97 row_ror:8 row_mask:0xf bank_mask:0xf
	v_mov_b32_e32 v111, v137
	v_cndmask_b32_e64 v99, v108, v100, s[4:5]
	v_mov_b32_e32 v106, v137
	v_mov_b32_dpp v107, v98 row_ror:8 row_mask:0xf bank_mask:0xf
	v_mov_b32_dpp v111, v96 row_ror:8 row_mask:0xf bank_mask:0xf
	v_cndmask_b32_e64 v98, v110, v104, s[4:5]
	v_or_b32_e32 v104, s22, v151
	v_mov_b32_dpp v106, v99 row_ror:8 row_mask:0xf bank_mask:0xf
	v_cndmask_b32_e64 v99, v111, v105, s[4:5]
	v_ashrrev_i32_e32 v105, 31, v104
	v_lshlrev_b64 v[104:105], 11, v[104:105]
	v_lshl_add_u64 v[104:105], s[30:31], 0, v[104:105]
	v_lshl_add_u64 v[104:105], v[146:147], 1, v[104:105]
	v_cndmask_b32_e64 v97, v107, v109, s[4:5]
	v_cndmask_b32_e64 v96, v106, v108, s[4:5]
	v_lshl_add_u64 v[104:105], v[104:105], 0, v[136:137]
	global_store_dwordx4 v[104:105], v[96:99], off nt
	v_cndmask_b32_e64 v103, v103, v111, s[4:5]
	v_cndmask_b32_e64 v102, v102, v110, s[4:5]
	v_add_co_u32_e32 v96, vcc, s52, v104
	v_cndmask_b32_e64 v101, v101, v107, s[4:5]
	v_cndmask_b32_e64 v100, v100, v106, s[4:5]
	v_addc_co_u32_e32 v97, vcc, 0, v105, vcc
	s_or_b32 s22, s19, 32
	global_store_dwordx4 v[96:97], v[100:103], off nt
	v_or_b32_e32 v96, s22, v150
	v_ashrrev_i32_e32 v97, 31, v96
	v_readlane_b32 s64, v239, 10
	v_lshlrev_b64 v[98:99], 12, v[96:97]
	v_readlane_b32 s65, v239, 11
	v_readlane_b32 s66, v239, 12
	v_readlane_b32 s67, v239, 13
	v_lshl_add_u64 v[98:99], s[64:65], 0, v[98:99]
	v_lshl_add_u64 v[110:111], v[146:147], 2, v[98:99]
	s_nop 0
	v_readlane_b32 s68, v239, 14
	v_readlane_b32 s69, v239, 15
	v_readlane_b32 s70, v239, 16
	v_readlane_b32 s71, v239, 17
	v_readlane_b32 s72, v239, 18
	v_readlane_b32 s73, v239, 19
	v_readlane_b32 s74, v239, 20
	v_readlane_b32 s75, v239, 21
	v_readlane_b32 s76, v239, 22
	v_readlane_b32 s77, v239, 23
	v_readlane_b32 s78, v239, 24
	v_readlane_b32 s79, v239, 25
	s_waitcnt vmcnt(18)
	v_mov_b64_e32 v[98:99], v[212:213]
	v_mov_b64_e32 v[100:101], v[214:215]
	v_mov_b64_e32 v[102:103], v[216:217]
	v_mov_b64_e32 v[104:105], v[218:219]
	v_mov_b64_e32 v[106:107], v[220:221]
	v_mov_b64_e32 v[108:109], v[222:223]
	v_mov_b64_e32 v[110:111], v[224:225]
	v_mov_b64_e32 v[112:113], v[226:227]
	s_mov_b32 s98, 0xa0000
	v_lshl_add_u64 v[232:233], v[234:235], 0, s[98:99]
	global_load_dwordx4 v[212:215], v[232:233], off
	global_load_dwordx4 v[216:219], v[232:233], off offset:16
	global_load_dwordx4 v[220:223], v[232:233], off offset:128
	global_load_dwordx4 v[224:227], v[232:233], off offset:144
	v_pk_add_f32 v[94:95], v[94:95], v[100:101]
	v_pk_add_f32 v[92:93], v[92:93], v[98:99]
	v_pk_add_f32 v[90:91], v[90:91], v[104:105]
	v_pk_add_f32 v[88:89], v[88:89], v[102:103]
	v_pk_add_f32 v[86:87], v[86:87], v[108:109]
	v_pk_add_f32 v[84:85], v[84:85], v[106:107]
	v_pk_add_f32 v[82:83], v[82:83], v[112:113]
	v_pk_add_f32 v[80:81], v[80:81], v[110:111]
	v_mul_f32_e32 v98, v93, v93
	v_mul_f32_e32 v99, v95, v95
	v_mul_f32_e32 v100, v89, v89
	v_mul_f32_e32 v101, v91, v91
	v_mul_f32_e32 v102, v85, v85
	v_mul_f32_e32 v103, v87, v87
	v_mul_f32_e32 v104, v81, v81
	v_mul_f32_e32 v105, v83, v83
	v_fmac_f32_e32 v98, v92, v92
	v_fmac_f32_e32 v99, v94, v94
	v_fmac_f32_e32 v100, v88, v88
	v_fmac_f32_e32 v101, v90, v90
	v_fmac_f32_e32 v102, v84, v84
	v_fmac_f32_e32 v103, v86, v86
	v_fmac_f32_e32 v104, v80, v80
	v_fmac_f32_e32 v105, v82, v82
	v_add_f32_e32 v98, v98, v99
	v_add_f32_e32 v99, v100, v101
	v_add_f32_e32 v100, v102, v103
	v_add_f32_e32 v101, v104, v105
	v_add_f32_e32 v98, v98, v99
	v_add_f32_e32 v99, v100, v101
	v_add_f32_e32 v98, v98, v99
	ds_bpermute_b32 v99, v161, v98
	s_waitcnt lgkmcnt(0)
	v_add_f32_e32 v98, v98, v99
	ds_bpermute_b32 v99, v162, v98
	s_and_saveexec_b64 s[20:21], s[2:3]
	s_cbranch_execz .LBB0_594
	v_lshlrev_b64 v[96:97], 6, v[96:97]
	v_lshl_add_u64 v[96:97], s[82:83], 0, v[96:97]
	v_lshl_add_u64 v[96:97], s[0:1], 2, v[96:97]
	s_lshl_b32 s10, s55, 2
	v_lshl_add_u64 v[96:97], v[96:97], 0, s[10:11]
	s_waitcnt lgkmcnt(0)
	v_add_f32_e32 v98, v98, v99
	global_store_dword v[96:97], v98, off
; __device__ __forceinline__ unsigned cvt_pk_bf16(float lo, float hi) { const cvt_f32x2_t v = {lo, hi}; const cvt_bf16x2_t b = __builtin_convertvector(v, cvt_bf16x2_t); return __builtin_bit_cast(unsigned, b); }
; __device__ __forceinline__ void wide_store(bf16_t* O, int ldc, int rowg  , int col0  , int fr, u32x4 w0, u32x4 w1) {
;     const bool lo = fr < 8;
;     u32x4 snd = lo ? w1 : w0, rcv;
;     rcv.x = swap8(snd.x); rcv.y = swap8(snd.y); rcv.z = swap8(snd.z); rcv.w = swap8(snd.w);
;     const u32x4 first = lo ? w0 : rcv, second = lo ? rcv : w1;
;     bf16_t* p = O + (size_t)(rowg + (fr & 7)) * ldc + col0 + (lo ? 0 : 32);
;     __builtin_nontemporal_store(first, (u32x4*)p); __builtin_nontemporal_store(second, (u32x4*)(p + (size_t)8 * ldc));
; }
;     __device__ __forceinline__ void operator()(const f32x4 (&acc)[2][2][4][2], const Unit& u, int wr, int wc, int fr, int fq) const {
;     ...
;             for (int m = 0; m < 4; ++m) { const int rowg = u.pm * BM + ai * HALF + wr * 64 + m * 16, row = rowg + fr; const size_t off = (size_t)row * 1024 + col0;
;                 u32x4 w[2]; float ss = 0.f;
; #pragma unroll
;                 for (int bj = 0; bj < 2; ++bj) { f32x4 b0, b1;
;                     if (BASE_F32) { const float* bp = (const float*)base + off + 32 * bj; b0 = *(const f32x4*)bp; b1 = *(const f32x4*)(bp + 4); }
;                     else { const u32x4 bb = *(const u32x4*)((const bf16_t*)base + off + 32 * bj);
;                         b0 = (f32x4){__uint_as_float(bb.x << 16), __uint_as_float(bb.x & 0xffff0000u), __uint_as_float(bb.y << 16), __uint_as_float(bb.y & 0xffff0000u)};
;                         b1 = (f32x4){__uint_as_float(bb.z << 16), __uint_as_float(bb.z & 0xffff0000u), __uint_as_float(bb.w << 16), __uint_as_float(bb.w & 0xffff0000u)}; }
;                     const f32x4 o0 = b0 + acc[ai][bj][m][0], o1 = b1 + acc[ai][bj][m][1];
;                     ss += ((o0[0] * o0[0] + o0[1] * o0[1]) + (o0[2] * o0[2] + o0[3] * o0[3])) + ((o1[0] * o1[0] + o1[1] * o1[1]) + (o1[2] * o1[2] + o1[3] * o1[3]));
;                     w[bj].x = cvt_pk_bf16(o0[0], o0[1]); w[bj].y = cvt_pk_bf16(o0[2], o0[3]); w[bj].z = cvt_pk_bf16(o1[0], o1[1]); w[bj].w = cvt_pk_bf16(o1[2], o1[3]); }
;                 ss += __shfl_xor(ss, 16); ss += __shfl_xor(ss, 32); if (fq == 0) slots[(size_t)row * 16 + u.pn * 4 + wc] = ss;
.LBB0_594:
	s_or_b64 exec, exec, s[20:21]
	v_cvt_pk_bf16_f32 v88, v88, v89
	v_cvt_pk_bf16_f32 v84, v84, v85
	v_cvt_pk_bf16_f32 v85, v86, v87
	v_cvt_pk_bf16_f32 v86, v80, v81
	v_cvt_pk_bf16_f32 v92, v92, v93
	v_cvt_pk_bf16_f32 v93, v94, v95
	v_cvt_pk_bf16_f32 v89, v90, v91
	v_cvt_pk_bf16_f32 v87, v82, v83
	v_cndmask_b32_e64 v81, v88, v86, s[4:5]
	v_mov_b32_e32 v94, v137
	v_cndmask_b32_e64 v80, v89, v87, s[4:5]
	v_cndmask_b32_e64 v82, v93, v85, s[4:5]
	v_mov_b32_e32 v91, v137
	v_mov_b32_dpp v94, v81 row_ror:8 row_mask:0xf bank_mask:0xf
	v_mov_b32_e32 v95, v137
	v_cndmask_b32_e64 v83, v92, v84, s[4:5]
	v_mov_b32_e32 v90, v137
	v_mov_b32_dpp v91, v82 row_ror:8 row_mask:0xf bank_mask:0xf
	v_mov_b32_dpp v95, v80 row_ror:8 row_mask:0xf bank_mask:0xf
	v_cndmask_b32_e64 v82, v94, v88, s[4:5]
	v_or_b32_e32 v88, s22, v151
	v_mov_b32_dpp v90, v83 row_ror:8 row_mask:0xf bank_mask:0xf
	v_cndmask_b32_e64 v83, v95, v89, s[4:5]
	v_ashrrev_i32_e32 v89, 31, v88
	v_lshlrev_b64 v[88:89], 11, v[88:89]
	v_lshl_add_u64 v[88:89], s[30:31], 0, v[88:89]
	v_lshl_add_u64 v[88:89], v[146:147], 1, v[88:89]
	v_cndmask_b32_e64 v81, v91, v93, s[4:5]
	v_cndmask_b32_e64 v80, v90, v92, s[4:5]
	v_lshl_add_u64 v[88:89], v[88:89], 0, v[136:137]
	global_store_dwordx4 v[88:89], v[80:83], off nt
	v_cndmask_b32_e64 v87, v87, v95, s[4:5]
	v_cndmask_b32_e64 v86, v86, v94, s[4:5]
	v_add_co_u32_e32 v80, vcc, s52, v88
	v_cndmask_b32_e64 v85, v85, v91, s[4:5]
	v_cndmask_b32_e64 v84, v84, v90, s[4:5]
	v_addc_co_u32_e32 v81, vcc, 0, v89, vcc
	s_or_b32 s22, s19, 48
	global_store_dwordx4 v[80:81], v[84:87], off nt
	v_or_b32_e32 v80, s22, v150
	v_ashrrev_i32_e32 v81, 31, v80
	v_readlane_b32 s64, v239, 10
	v_lshlrev_b64 v[82:83], 12, v[80:81]
	v_readlane_b32 s65, v239, 11
	v_readlane_b32 s66, v239, 12
	v_readlane_b32 s67, v239, 13
	v_lshl_add_u64 v[82:83], s[64:65], 0, v[82:83]
	v_lshl_add_u64 v[94:95], v[146:147], 2, v[82:83]
	s_nop 0
	v_readlane_b32 s68, v239, 14
	v_readlane_b32 s69, v239, 15
	v_readlane_b32 s70, v239, 16
	v_readlane_b32 s71, v239, 17
	v_readlane_b32 s72, v239, 18
	v_readlane_b32 s73, v239, 19
	v_readlane_b32 s74, v239, 20
	v_readlane_b32 s75, v239, 21
	v_readlane_b32 s76, v239, 22
	v_readlane_b32 s77, v239, 23
	v_readlane_b32 s78, v239, 24
	v_readlane_b32 s79, v239, 25
	s_waitcnt vmcnt(21)
	v_mov_b64_e32 v[82:83], v[240:241]
	v_mov_b64_e32 v[84:85], v[242:243]
	v_mov_b64_e32 v[86:87], v[244:245]
	v_mov_b64_e32 v[88:89], v[246:247]
	v_mov_b64_e32 v[90:91], v[248:249]
	v_mov_b64_e32 v[92:93], v[250:251]
	v_mov_b64_e32 v[94:95], v[252:253]
	v_mov_b64_e32 v[96:97], v[254:255]
	s_mov_b32 s98, 0xb0000
	v_lshl_add_u64 v[232:233], v[234:235], 0, s[98:99]
	global_load_dwordx4 v[240:243], v[232:233], off
	global_load_dwordx4 v[244:247], v[232:233], off offset:16
	global_load_dwordx4 v[248:251], v[232:233], off offset:128
	global_load_dwordx4 v[252:255], v[232:233], off offset:144
	v_pk_add_f32 v[78:79], v[78:79], v[84:85]
	v_pk_add_f32 v[76:77], v[76:77], v[82:83]
	v_pk_add_f32 v[74:75], v[74:75], v[88:89]
	v_pk_add_f32 v[72:73], v[72:73], v[86:87]
	v_pk_add_f32 v[70:71], v[70:71], v[92:93]
	v_pk_add_f32 v[68:69], v[68:69], v[90:91]
	v_pk_add_f32 v[66:67], v[66:67], v[96:97]
	v_pk_add_f32 v[64:65], v[64:65], v[94:95]
	v_mul_f32_e32 v82, v77, v77
	v_mul_f32_e32 v83, v79, v79
	v_mul_f32_e32 v84, v73, v73
	v_mul_f32_e32 v85, v75, v75
	v_mul_f32_e32 v86, v69, v69
	v_mul_f32_e32 v87, v71, v71
	v_mul_f32_e32 v88, v65, v65
	v_mul_f32_e32 v89, v67, v67
	v_fmac_f32_e32 v82, v76, v76
	v_fmac_f32_e32 v83, v78, v78
	v_fmac_f32_e32 v84, v72, v72
	v_fmac_f32_e32 v85, v74, v74
	v_fmac_f32_e32 v86, v68, v68
	v_fmac_f32_e32 v87, v70, v70
	v_fmac_f32_e32 v88, v64, v64
	v_fmac_f32_e32 v89, v66, v66
	v_add_f32_e32 v82, v82, v83
	v_add_f32_e32 v83, v84, v85
	v_add_f32_e32 v84, v86, v87
	v_add_f32_e32 v85, v88, v89
	v_add_f32_e32 v82, v82, v83
	v_add_f32_e32 v83, v84, v85
	v_add_f32_e32 v82, v82, v83
	ds_bpermute_b32 v83, v161, v82
	s_waitcnt lgkmcnt(0)
	v_add_f32_e32 v82, v82, v83
	ds_bpermute_b32 v83, v162, v82
	s_and_saveexec_b64 s[20:21], s[2:3]
	s_cbranch_execz .LBB0_596
	v_lshlrev_b64 v[80:81], 6, v[80:81]
	v_lshl_add_u64 v[80:81], s[82:83], 0, v[80:81]
	v_lshl_add_u64 v[80:81], s[0:1], 2, v[80:81]
	s_lshl_b32 s10, s55, 2
	v_lshl_add_u64 v[80:81], v[80:81], 0, s[10:11]
	s_waitcnt lgkmcnt(0)
	v_add_f32_e32 v82, v82, v83
	global_store_dword v[80:81], v82, off
; __device__ __forceinline__ unsigned cvt_pk_bf16(float lo, float hi) { const cvt_f32x2_t v = {lo, hi}; const cvt_bf16x2_t b = __builtin_convertvector(v, cvt_bf16x2_t); return __builtin_bit_cast(unsigned, b); }
; __device__ __forceinline__ void wide_store(bf16_t* O, int ldc, int rowg  , int col0  , int fr, u32x4 w0, u32x4 w1) {
;     const bool lo = fr < 8;
;     u32x4 snd = lo ? w1 : w0, rcv;
;     rcv.x = swap8(snd.x); rcv.y = swap8(snd.y); rcv.z = swap8(snd.z); rcv.w = swap8(snd.w);
;     const u32x4 first = lo ? w0 : rcv, second = lo ? rcv : w1;
;     bf16_t* p = O + (size_t)(rowg + (fr & 7)) * ldc + col0 + (lo ? 0 : 32);
;     __builtin_nontemporal_store(first, (u32x4*)p); __builtin_nontemporal_store(second, (u32x4*)(p + (size_t)8 * ldc));
; }
;     __device__ __forceinline__ void operator()(const f32x4 (&acc)[2][2][4][2], const Unit& u, int wr, int wc, int fr, int fq) const {
;     ...
;             for (int m = 0; m < 4; ++m) { const int rowg = u.pm * BM + ai * HALF + wr * 64 + m * 16, row = rowg + fr; const size_t off = (size_t)row * 1024 + col0;
;                 u32x4 w[2]; float ss = 0.f;
; #pragma unroll
;                 for (int bj = 0; bj < 2; ++bj) { f32x4 b0, b1;
;                     if (BASE_F32) { const float* bp = (const float*)base + off + 32 * bj; b0 = *(const f32x4*)bp; b1 = *(const f32x4*)(bp + 4); }
;                     else { const u32x4 bb = *(const u32x4*)((const bf16_t*)base + off + 32 * bj);
;                         b0 = (f32x4){__uint_as_float(bb.x << 16), __uint_as_float(bb.x & 0xffff0000u), __uint_as_float(bb.y << 16), __uint_as_float(bb.y & 0xffff0000u)};
;                         b1 = (f32x4){__uint_as_float(bb.z << 16), __uint_as_float(bb.z & 0xffff0000u), __uint_as_float(bb.w << 16), __uint_as_float(bb.w & 0xffff0000u)}; }
;                     const f32x4 o0 = b0 + acc[ai][bj][m][0], o1 = b1 + acc[ai][bj][m][1];
;                     ss += ((o0[0] * o0[0] + o0[1] * o0[1]) + (o0[2] * o0[2] + o0[3] * o0[3])) + ((o1[0] * o1[0] + o1[1] * o1[1]) + (o1[2] * o1[2] + o1[3] * o1[3]));
;                     w[bj].x = cvt_pk_bf16(o0[0], o0[1]); w[bj].y = cvt_pk_bf16(o0[2], o0[3]); w[bj].z = cvt_pk_bf16(o1[0], o1[1]); w[bj].w = cvt_pk_bf16(o1[2], o1[3]); }
;                 ss += __shfl_xor(ss, 16); ss += __shfl_xor(ss, 32); if (fq == 0) slots[(size_t)row * 16 + u.pn * 4 + wc] = ss;
.LBB0_596:
	s_or_b64 exec, exec, s[20:21]
	v_cvt_pk_bf16_f32 v72, v72, v73
	v_cvt_pk_bf16_f32 v68, v68, v69
	v_cvt_pk_bf16_f32 v69, v70, v71
	v_cvt_pk_bf16_f32 v70, v64, v65
	v_cvt_pk_bf16_f32 v76, v76, v77
	v_cvt_pk_bf16_f32 v77, v78, v79
	v_cvt_pk_bf16_f32 v73, v74, v75
	v_cvt_pk_bf16_f32 v71, v66, v67
	v_cndmask_b32_e64 v65, v72, v70, s[4:5]
	v_mov_b32_e32 v78, v137
	v_cndmask_b32_e64 v64, v73, v71, s[4:5]
	v_cndmask_b32_e64 v66, v77, v69, s[4:5]
	v_mov_b32_e32 v75, v137
	v_mov_b32_dpp v78, v65 row_ror:8 row_mask:0xf bank_mask:0xf
	v_mov_b32_e32 v79, v137
	v_cndmask_b32_e64 v67, v76, v68, s[4:5]
	v_mov_b32_e32 v74, v137
	v_mov_b32_dpp v75, v66 row_ror:8 row_mask:0xf bank_mask:0xf
	v_mov_b32_dpp v79, v64 row_ror:8 row_mask:0xf bank_mask:0xf
	v_cndmask_b32_e64 v66, v78, v72, s[4:5]
	v_or_b32_e32 v72, s22, v151
	v_mov_b32_dpp v74, v67 row_ror:8 row_mask:0xf bank_mask:0xf
	v_cndmask_b32_e64 v67, v79, v73, s[4:5]
	v_ashrrev_i32_e32 v73, 31, v72
	v_lshlrev_b64 v[72:73], 11, v[72:73]
	v_lshl_add_u64 v[72:73], s[30:31], 0, v[72:73]
	v_lshl_add_u64 v[72:73], v[146:147], 1, v[72:73]
	v_cndmask_b32_e64 v65, v75, v77, s[4:5]
	v_cndmask_b32_e64 v64, v74, v76, s[4:5]
	v_lshl_add_u64 v[72:73], v[72:73], 0, v[136:137]
	global_store_dwordx4 v[72:73], v[64:67], off nt
	v_cndmask_b32_e64 v71, v71, v79, s[4:5]
	v_cndmask_b32_e64 v70, v70, v78, s[4:5]
	v_add_co_u32_e32 v64, vcc, s52, v72
	v_cndmask_b32_e64 v69, v69, v75, s[4:5]
	v_cndmask_b32_e64 v68, v68, v74, s[4:5]
	v_addc_co_u32_e32 v65, vcc, 0, v73, vcc
	s_add_i32 s22, s19, 0x80
	global_store_dwordx4 v[64:65], v[68:71], off nt
	v_or_b32_e32 v64, s22, v150
	v_ashrrev_i32_e32 v65, 31, v64
	v_readlane_b32 s64, v239, 10
	v_lshlrev_b64 v[66:67], 12, v[64:65]
	v_readlane_b32 s65, v239, 11
	v_readlane_b32 s66, v239, 12
	v_readlane_b32 s67, v239, 13
	v_lshl_add_u64 v[66:67], s[64:65], 0, v[66:67]
	v_lshl_add_u64 v[78:79], v[146:147], 2, v[66:67]
	s_nop 0
	v_readlane_b32 s68, v239, 14
	v_readlane_b32 s69, v239, 15
	v_readlane_b32 s70, v239, 16
	v_readlane_b32 s71, v239, 17
	v_readlane_b32 s72, v239, 18
	v_readlane_b32 s73, v239, 19
	v_readlane_b32 s74, v239, 20
	v_readlane_b32 s75, v239, 21
	v_readlane_b32 s76, v239, 22
	v_readlane_b32 s77, v239, 23
	v_readlane_b32 s78, v239, 24
	v_readlane_b32 s79, v239, 25
	s_waitcnt vmcnt(24)
	v_mov_b64_e32 v[66:67], v[180:181]
	v_mov_b64_e32 v[68:69], v[182:183]
	v_mov_b64_e32 v[70:71], v[184:185]
	v_mov_b64_e32 v[72:73], v[186:187]
	v_mov_b64_e32 v[74:75], v[188:189]
	v_mov_b64_e32 v[76:77], v[190:191]
	v_mov_b64_e32 v[78:79], v[192:193]
	v_mov_b64_e32 v[80:81], v[194:195]
	v_pk_add_f32 v[62:63], v[62:63], v[68:69]
	v_pk_add_f32 v[60:61], v[60:61], v[66:67]
	v_pk_add_f32 v[58:59], v[58:59], v[72:73]
	v_pk_add_f32 v[56:57], v[56:57], v[70:71]
	v_pk_add_f32 v[54:55], v[54:55], v[76:77]
	v_pk_add_f32 v[52:53], v[52:53], v[74:75]
	v_pk_add_f32 v[50:51], v[50:51], v[80:81]
	v_pk_add_f32 v[48:49], v[48:49], v[78:79]
	v_mul_f32_e32 v66, v61, v61
	v_mul_f32_e32 v67, v63, v63
	v_mul_f32_e32 v68, v57, v57
	v_mul_f32_e32 v69, v59, v59
	v_mul_f32_e32 v70, v53, v53
	v_mul_f32_e32 v71, v55, v55
	v_mul_f32_e32 v72, v49, v49
	v_mul_f32_e32 v73, v51, v51
	v_fmac_f32_e32 v66, v60, v60
	v_fmac_f32_e32 v67, v62, v62
	v_fmac_f32_e32 v68, v56, v56
	v_fmac_f32_e32 v69, v58, v58
	v_fmac_f32_e32 v70, v52, v52
	v_fmac_f32_e32 v71, v54, v54
	v_fmac_f32_e32 v72, v48, v48
	v_fmac_f32_e32 v73, v50, v50
	v_add_f32_e32 v66, v66, v67
	v_add_f32_e32 v67, v68, v69
	v_add_f32_e32 v68, v70, v71
	v_add_f32_e32 v69, v72, v73
	v_add_f32_e32 v66, v66, v67
	v_add_f32_e32 v67, v68, v69
	v_add_f32_e32 v66, v66, v67
	ds_bpermute_b32 v67, v161, v66
	s_waitcnt lgkmcnt(0)
	v_add_f32_e32 v66, v66, v67
	ds_bpermute_b32 v67, v162, v66
	s_and_saveexec_b64 s[20:21], s[2:3]
	s_cbranch_execz .LBB0_598
	v_lshlrev_b64 v[64:65], 6, v[64:65]
	v_lshl_add_u64 v[64:65], s[82:83], 0, v[64:65]
	v_lshl_add_u64 v[64:65], s[0:1], 2, v[64:65]
	s_lshl_b32 s10, s55, 2
	v_lshl_add_u64 v[64:65], v[64:65], 0, s[10:11]
	s_waitcnt lgkmcnt(0)
	v_add_f32_e32 v66, v66, v67
	global_store_dword v[64:65], v66, off
.LBB0_598:
	s_or_b64 exec, exec, s[20:21]
	v_cvt_pk_bf16_f32 v56, v56, v57
	v_cvt_pk_bf16_f32 v52, v52, v53
	v_cvt_pk_bf16_f32 v53, v54, v55
	v_cvt_pk_bf16_f32 v54, v48, v49
	v_cvt_pk_bf16_f32 v60, v60, v61
	v_cvt_pk_bf16_f32 v61, v62, v63
	v_cvt_pk_bf16_f32 v57, v58, v59
	v_cvt_pk_bf16_f32 v55, v50, v51
	v_cndmask_b32_e64 v49, v56, v54, s[4:5]
	v_mov_b32_e32 v62, v137
	v_cndmask_b32_e64 v48, v57, v55, s[4:5]
	v_cndmask_b32_e64 v50, v61, v53, s[4:5]
	v_mov_b32_e32 v59, v137
	v_mov_b32_dpp v62, v49 row_ror:8 row_mask:0xf bank_mask:0xf
	v_mov_b32_e32 v63, v137
	v_cndmask_b32_e64 v51, v60, v52, s[4:5]
	v_mov_b32_e32 v58, v137
	v_mov_b32_dpp v59, v50 row_ror:8 row_mask:0xf bank_mask:0xf
	v_mov_b32_dpp v63, v48 row_ror:8 row_mask:0xf bank_mask:0xf
	v_cndmask_b32_e64 v50, v62, v56, s[4:5]
	v_or_b32_e32 v56, s22, v151
	v_mov_b32_dpp v58, v51 row_ror:8 row_mask:0xf bank_mask:0xf
	v_cndmask_b32_e64 v51, v63, v57, s[4:5]
	v_ashrrev_i32_e32 v57, 31, v56
	v_lshlrev_b64 v[56:57], 11, v[56:57]
	v_lshl_add_u64 v[56:57], s[30:31], 0, v[56:57]
	v_lshl_add_u64 v[56:57], v[146:147], 1, v[56:57]
	v_cndmask_b32_e64 v49, v59, v61, s[4:5]
	v_cndmask_b32_e64 v48, v58, v60, s[4:5]
	v_lshl_add_u64 v[56:57], v[56:57], 0, v[136:137]
	global_store_dwordx4 v[56:57], v[48:51], off nt
	v_cndmask_b32_e64 v55, v55, v63, s[4:5]
	v_cndmask_b32_e64 v54, v54, v62, s[4:5]
	v_add_co_u32_e32 v48, vcc, s52, v56
	v_cndmask_b32_e64 v53, v53, v59, s[4:5]
	v_cndmask_b32_e64 v52, v52, v58, s[4:5]
	v_addc_co_u32_e32 v49, vcc, 0, v57, vcc
	s_add_i32 s22, s19, 0x90
	global_store_dwordx4 v[48:49], v[52:55], off nt
	v_or_b32_e32 v48, s22, v150
	v_ashrrev_i32_e32 v49, 31, v48
	v_readlane_b32 s64, v239, 10
	v_lshlrev_b64 v[50:51], 12, v[48:49]
	v_readlane_b32 s65, v239, 11
	v_readlane_b32 s66, v239, 12
	v_readlane_b32 s67, v239, 13
	v_lshl_add_u64 v[50:51], s[64:65], 0, v[50:51]
	v_lshl_add_u64 v[62:63], v[146:147], 2, v[50:51]
	s_nop 0
	v_readlane_b32 s68, v239, 14
	v_readlane_b32 s69, v239, 15
	v_readlane_b32 s70, v239, 16
	v_readlane_b32 s71, v239, 17
	v_readlane_b32 s72, v239, 18
	v_readlane_b32 s73, v239, 19
	v_readlane_b32 s74, v239, 20
	v_readlane_b32 s75, v239, 21
	v_readlane_b32 s76, v239, 22
	v_readlane_b32 s77, v239, 23
	v_readlane_b32 s78, v239, 24
	v_readlane_b32 s79, v239, 25
	s_waitcnt vmcnt(20)
; __device__ __forceinline__ unsigned cvt_pk_bf16(float lo, float hi) { const cvt_f32x2_t v = {lo, hi}; const cvt_bf16x2_t b = __builtin_convertvector(v, cvt_bf16x2_t); return __builtin_bit_cast(unsigned, b); }
; __device__ __forceinline__ void wide_store(bf16_t* O, int ldc, int rowg  , int col0  , int fr, u32x4 w0, u32x4 w1) {
;     const bool lo = fr < 8;
;     u32x4 snd = lo ? w1 : w0, rcv;
;     rcv.x = swap8(snd.x); rcv.y = swap8(snd.y); rcv.z = swap8(snd.z); rcv.w = swap8(snd.w);
;     const u32x4 first = lo ? w0 : rcv, second = lo ? rcv : w1;
;     bf16_t* p = O + (size_t)(rowg + (fr & 7)) * ldc + col0 + (lo ? 0 : 32);
;     __builtin_nontemporal_store(first, (u32x4*)p); __builtin_nontemporal_store(second, (u32x4*)(p + (size_t)8 * ldc));
; }
;     __device__ __forceinline__ void operator()(const f32x4 (&acc)[2][2][4][2], const Unit& u, int wr, int wc, int fr, int fq) const {
;     ...
;             for (int m = 0; m < 4; ++m) { const int rowg = u.pm * BM + ai * HALF + wr * 64 + m * 16, row = rowg + fr; const size_t off = (size_t)row * 1024 + col0;
;                 u32x4 w[2]; float ss = 0.f;
; #pragma unroll
;                 for (int bj = 0; bj < 2; ++bj) { f32x4 b0, b1;
;                     if (BASE_F32) { const float* bp = (const float*)base + off + 32 * bj; b0 = *(const f32x4*)bp; b1 = *(const f32x4*)(bp + 4); }
;                     else { const u32x4 bb = *(const u32x4*)((const bf16_t*)base + off + 32 * bj);
;                         b0 = (f32x4){__uint_as_float(bb.x << 16), __uint_as_float(bb.x & 0xffff0000u), __uint_as_float(bb.y << 16), __uint_as_float(bb.y & 0xffff0000u)};
;                         b1 = (f32x4){__uint_as_float(bb.z << 16), __uint_as_float(bb.z & 0xffff0000u), __uint_as_float(bb.w << 16), __uint_as_float(bb.w & 0xffff0000u)}; }
;                     const f32x4 o0 = b0 + acc[ai][bj][m][0], o1 = b1 + acc[ai][bj][m][1];
;                     ss += ((o0[0] * o0[0] + o0[1] * o0[1]) + (o0[2] * o0[2] + o0[3] * o0[3])) + ((o1[0] * o1[0] + o1[1] * o1[1]) + (o1[2] * o1[2] + o1[3] * o1[3]));
;                     w[bj].x = cvt_pk_bf16(o0[0], o0[1]); w[bj].y = cvt_pk_bf16(o0[2], o0[3]); w[bj].z = cvt_pk_bf16(o1[0], o1[1]); w[bj].w = cvt_pk_bf16(o1[2], o1[3]); }
;                 ss += __shfl_xor(ss, 16); ss += __shfl_xor(ss, 32); if (fq == 0) slots[(size_t)row * 16 + u.pn * 4 + wc] = ss;
	v_mov_b64_e32 v[50:51], v[196:197]
	v_mov_b64_e32 v[52:53], v[198:199]
	v_mov_b64_e32 v[54:55], v[200:201]
	v_mov_b64_e32 v[56:57], v[202:203]
	v_mov_b64_e32 v[58:59], v[204:205]
	v_mov_b64_e32 v[60:61], v[206:207]
	v_mov_b64_e32 v[62:63], v[208:209]
	v_mov_b64_e32 v[64:65], v[210:211]
	v_pk_add_f32 v[46:47], v[46:47], v[52:53]
	v_pk_add_f32 v[44:45], v[44:45], v[50:51]
	v_pk_add_f32 v[42:43], v[42:43], v[56:57]
	v_pk_add_f32 v[40:41], v[40:41], v[54:55]
	v_pk_add_f32 v[38:39], v[38:39], v[60:61]
	v_pk_add_f32 v[36:37], v[36:37], v[58:59]
	v_pk_add_f32 v[34:35], v[34:35], v[64:65]
	v_pk_add_f32 v[32:33], v[32:33], v[62:63]
	v_mul_f32_e32 v50, v45, v45
	v_mul_f32_e32 v51, v47, v47
	v_mul_f32_e32 v52, v41, v41
	v_mul_f32_e32 v53, v43, v43
	v_mul_f32_e32 v54, v37, v37
	v_mul_f32_e32 v55, v39, v39
	v_mul_f32_e32 v56, v33, v33
	v_mul_f32_e32 v57, v35, v35
	v_fmac_f32_e32 v50, v44, v44
	v_fmac_f32_e32 v51, v46, v46
	v_fmac_f32_e32 v52, v40, v40
	v_fmac_f32_e32 v53, v42, v42
	v_fmac_f32_e32 v54, v36, v36
	v_fmac_f32_e32 v55, v38, v38
	v_fmac_f32_e32 v56, v32, v32
	v_fmac_f32_e32 v57, v34, v34
	v_add_f32_e32 v50, v50, v51
	v_add_f32_e32 v51, v52, v53
	v_add_f32_e32 v52, v54, v55
	v_add_f32_e32 v53, v56, v57
	v_add_f32_e32 v50, v50, v51
	v_add_f32_e32 v51, v52, v53
	v_add_f32_e32 v50, v50, v51
	ds_bpermute_b32 v51, v161, v50
	s_waitcnt lgkmcnt(0)
	v_add_f32_e32 v50, v50, v51
	ds_bpermute_b32 v51, v162, v50
	s_and_saveexec_b64 s[20:21], s[2:3]
	s_cbranch_execz .LBB0_600
	v_lshlrev_b64 v[48:49], 6, v[48:49]
	v_lshl_add_u64 v[48:49], s[82:83], 0, v[48:49]
	v_lshl_add_u64 v[48:49], s[0:1], 2, v[48:49]
	s_lshl_b32 s10, s55, 2
	v_lshl_add_u64 v[48:49], v[48:49], 0, s[10:11]
	s_waitcnt lgkmcnt(0)
	v_add_f32_e32 v50, v50, v51
	global_store_dword v[48:49], v50, off
.LBB0_600:
	s_or_b64 exec, exec, s[20:21]
	v_cvt_pk_bf16_f32 v40, v40, v41
	v_cvt_pk_bf16_f32 v36, v36, v37
	v_cvt_pk_bf16_f32 v37, v38, v39
	v_cvt_pk_bf16_f32 v38, v32, v33
	v_cvt_pk_bf16_f32 v44, v44, v45
	v_cvt_pk_bf16_f32 v45, v46, v47
	v_cvt_pk_bf16_f32 v41, v42, v43
	v_cvt_pk_bf16_f32 v39, v34, v35
	v_cndmask_b32_e64 v33, v40, v38, s[4:5]
	v_mov_b32_e32 v46, v137
	v_cndmask_b32_e64 v32, v41, v39, s[4:5]
	v_cndmask_b32_e64 v34, v45, v37, s[4:5]
	v_mov_b32_e32 v43, v137
	v_mov_b32_dpp v46, v33 row_ror:8 row_mask:0xf bank_mask:0xf
	v_mov_b32_e32 v47, v137
	v_cndmask_b32_e64 v35, v44, v36, s[4:5]
	v_mov_b32_e32 v42, v137
	v_mov_b32_dpp v43, v34 row_ror:8 row_mask:0xf bank_mask:0xf
	v_mov_b32_dpp v47, v32 row_ror:8 row_mask:0xf bank_mask:0xf
	v_cndmask_b32_e64 v34, v46, v40, s[4:5]
	v_or_b32_e32 v40, s22, v151
	v_mov_b32_dpp v42, v35 row_ror:8 row_mask:0xf bank_mask:0xf
	v_cndmask_b32_e64 v35, v47, v41, s[4:5]
	v_ashrrev_i32_e32 v41, 31, v40
	v_lshlrev_b64 v[40:41], 11, v[40:41]
	v_lshl_add_u64 v[40:41], s[30:31], 0, v[40:41]
	v_lshl_add_u64 v[40:41], v[146:147], 1, v[40:41]
	v_cndmask_b32_e64 v33, v43, v45, s[4:5]
	v_cndmask_b32_e64 v32, v42, v44, s[4:5]
	v_lshl_add_u64 v[40:41], v[40:41], 0, v[136:137]
	global_store_dwordx4 v[40:41], v[32:35], off nt
	v_cndmask_b32_e64 v39, v39, v47, s[4:5]
	v_cndmask_b32_e64 v38, v38, v46, s[4:5]
	v_add_co_u32_e32 v32, vcc, s52, v40
	v_cndmask_b32_e64 v37, v37, v43, s[4:5]
	v_cndmask_b32_e64 v36, v36, v42, s[4:5]
	v_addc_co_u32_e32 v33, vcc, 0, v41, vcc
	s_add_i32 s22, s19, 0xa0
	global_store_dwordx4 v[32:33], v[36:39], off nt
	v_or_b32_e32 v32, s22, v150
	v_ashrrev_i32_e32 v33, 31, v32
	v_readlane_b32 s64, v239, 10
	v_lshlrev_b64 v[34:35], 12, v[32:33]
	v_readlane_b32 s65, v239, 11
	v_readlane_b32 s66, v239, 12
	v_readlane_b32 s67, v239, 13
	v_lshl_add_u64 v[34:35], s[64:65], 0, v[34:35]
	v_lshl_add_u64 v[46:47], v[146:147], 2, v[34:35]
	s_nop 0
	v_readlane_b32 s68, v239, 14
	v_readlane_b32 s69, v239, 15
	v_readlane_b32 s70, v239, 16
	v_readlane_b32 s71, v239, 17
	v_readlane_b32 s72, v239, 18
	v_readlane_b32 s73, v239, 19
	v_readlane_b32 s74, v239, 20
	v_readlane_b32 s75, v239, 21
	v_readlane_b32 s76, v239, 22
	v_readlane_b32 s77, v239, 23
	v_readlane_b32 s78, v239, 24
	v_readlane_b32 s79, v239, 25
	s_waitcnt vmcnt(16)
	v_mov_b64_e32 v[34:35], v[212:213]
	v_mov_b64_e32 v[36:37], v[214:215]
	v_mov_b64_e32 v[38:39], v[216:217]
	v_mov_b64_e32 v[40:41], v[218:219]
	v_mov_b64_e32 v[42:43], v[220:221]
	v_mov_b64_e32 v[44:45], v[222:223]
	v_mov_b64_e32 v[46:47], v[224:225]
	v_mov_b64_e32 v[48:49], v[226:227]
	v_pk_add_f32 v[30:31], v[30:31], v[36:37]
	v_pk_add_f32 v[28:29], v[28:29], v[34:35]
	v_pk_add_f32 v[26:27], v[26:27], v[40:41]
	v_pk_add_f32 v[24:25], v[24:25], v[38:39]
	v_pk_add_f32 v[22:23], v[22:23], v[44:45]
	v_pk_add_f32 v[20:21], v[20:21], v[42:43]
	v_pk_add_f32 v[18:19], v[18:19], v[48:49]
	v_pk_add_f32 v[16:17], v[16:17], v[46:47]
	v_mul_f32_e32 v34, v29, v29
	v_mul_f32_e32 v35, v31, v31
	v_mul_f32_e32 v36, v25, v25
	v_mul_f32_e32 v37, v27, v27
	v_mul_f32_e32 v38, v21, v21
	v_mul_f32_e32 v39, v23, v23
	v_mul_f32_e32 v40, v17, v17
	v_mul_f32_e32 v41, v19, v19
	v_fmac_f32_e32 v34, v28, v28
	v_fmac_f32_e32 v35, v30, v30
	v_fmac_f32_e32 v36, v24, v24
	v_fmac_f32_e32 v37, v26, v26
	v_fmac_f32_e32 v38, v20, v20
	v_fmac_f32_e32 v39, v22, v22
	v_fmac_f32_e32 v40, v16, v16
	v_fmac_f32_e32 v41, v18, v18
	v_add_f32_e32 v34, v34, v35
	v_add_f32_e32 v35, v36, v37
	v_add_f32_e32 v36, v38, v39
	v_add_f32_e32 v37, v40, v41
	v_add_f32_e32 v34, v34, v35
	v_add_f32_e32 v35, v36, v37
	v_add_f32_e32 v34, v34, v35
	ds_bpermute_b32 v35, v161, v34
	s_waitcnt lgkmcnt(0)
	v_add_f32_e32 v34, v34, v35
	ds_bpermute_b32 v35, v162, v34
	s_and_saveexec_b64 s[20:21], s[2:3]
	s_cbranch_execz .LBB0_602
	v_lshlrev_b64 v[32:33], 6, v[32:33]
	v_lshl_add_u64 v[32:33], s[82:83], 0, v[32:33]
	v_lshl_add_u64 v[32:33], s[0:1], 2, v[32:33]
	s_lshl_b32 s10, s55, 2
	v_lshl_add_u64 v[32:33], v[32:33], 0, s[10:11]
	s_waitcnt lgkmcnt(0)
	v_add_f32_e32 v34, v34, v35
	global_store_dword v[32:33], v34, off
; __device__ __forceinline__ unsigned cvt_pk_bf16(float lo, float hi) { const cvt_f32x2_t v = {lo, hi}; const cvt_bf16x2_t b = __builtin_convertvector(v, cvt_bf16x2_t); return __builtin_bit_cast(unsigned, b); }
; __device__ __forceinline__ void wide_store(bf16_t* O, int ldc, int rowg  , int col0  , int fr, u32x4 w0, u32x4 w1) {
;     const bool lo = fr < 8;
;     u32x4 snd = lo ? w1 : w0, rcv;
;     rcv.x = swap8(snd.x); rcv.y = swap8(snd.y); rcv.z = swap8(snd.z); rcv.w = swap8(snd.w);
;     const u32x4 first = lo ? w0 : rcv, second = lo ? rcv : w1;
;     bf16_t* p = O + (size_t)(rowg + (fr & 7)) * ldc + col0 + (lo ? 0 : 32);
;     __builtin_nontemporal_store(first, (u32x4*)p); __builtin_nontemporal_store(second, (u32x4*)(p + (size_t)8 * ldc));
; }
;     __device__ __forceinline__ void operator()(const f32x4 (&acc)[2][2][4][2], const Unit& u, int wr, int wc, int fr, int fq) const {
;     ...
;             for (int m = 0; m < 4; ++m) { const int rowg = u.pm * BM + ai * HALF + wr * 64 + m * 16, row = rowg + fr; const size_t off = (size_t)row * 1024 + col0;
;                 u32x4 w[2]; float ss = 0.f;
; #pragma unroll
;                 for (int bj = 0; bj < 2; ++bj) { f32x4 b0, b1;
;                     if (BASE_F32) { const float* bp = (const float*)base + off + 32 * bj; b0 = *(const f32x4*)bp; b1 = *(const f32x4*)(bp + 4); }
;                     else { const u32x4 bb = *(const u32x4*)((const bf16_t*)base + off + 32 * bj);
;                         b0 = (f32x4){__uint_as_float(bb.x << 16), __uint_as_float(bb.x & 0xffff0000u), __uint_as_float(bb.y << 16), __uint_as_float(bb.y & 0xffff0000u)};
;                         b1 = (f32x4){__uint_as_float(bb.z << 16), __uint_as_float(bb.z & 0xffff0000u), __uint_as_float(bb.w << 16), __uint_as_float(bb.w & 0xffff0000u)}; }
;                     const f32x4 o0 = b0 + acc[ai][bj][m][0], o1 = b1 + acc[ai][bj][m][1];
;                     ss += ((o0[0] * o0[0] + o0[1] * o0[1]) + (o0[2] * o0[2] + o0[3] * o0[3])) + ((o1[0] * o1[0] + o1[1] * o1[1]) + (o1[2] * o1[2] + o1[3] * o1[3]));
;                     w[bj].x = cvt_pk_bf16(o0[0], o0[1]); w[bj].y = cvt_pk_bf16(o0[2], o0[3]); w[bj].z = cvt_pk_bf16(o1[0], o1[1]); w[bj].w = cvt_pk_bf16(o1[2], o1[3]); }
;                 ss += __shfl_xor(ss, 16); ss += __shfl_xor(ss, 32); if (fq == 0) slots[(size_t)row * 16 + u.pn * 4 + wc] = ss;
.LBB0_602:
	s_or_b64 exec, exec, s[20:21]
	v_cvt_pk_bf16_f32 v24, v24, v25
	v_cvt_pk_bf16_f32 v20, v20, v21
	v_cvt_pk_bf16_f32 v21, v22, v23
	v_cvt_pk_bf16_f32 v22, v16, v17
	v_cvt_pk_bf16_f32 v28, v28, v29
	v_cvt_pk_bf16_f32 v29, v30, v31
	v_cvt_pk_bf16_f32 v25, v26, v27
	v_cvt_pk_bf16_f32 v23, v18, v19
	v_cndmask_b32_e64 v17, v24, v22, s[4:5]
	v_mov_b32_e32 v30, v137
	v_cndmask_b32_e64 v16, v25, v23, s[4:5]
	v_cndmask_b32_e64 v18, v29, v21, s[4:5]
	v_mov_b32_e32 v27, v137
	v_mov_b32_dpp v30, v17 row_ror:8 row_mask:0xf bank_mask:0xf
	v_mov_b32_e32 v31, v137
	v_cndmask_b32_e64 v19, v28, v20, s[4:5]
	v_mov_b32_e32 v26, v137
	v_mov_b32_dpp v27, v18 row_ror:8 row_mask:0xf bank_mask:0xf
	v_mov_b32_dpp v31, v16 row_ror:8 row_mask:0xf bank_mask:0xf
	v_cndmask_b32_e64 v18, v30, v24, s[4:5]
	v_or_b32_e32 v24, s22, v151
	v_mov_b32_dpp v26, v19 row_ror:8 row_mask:0xf bank_mask:0xf
	v_cndmask_b32_e64 v19, v31, v25, s[4:5]
	v_ashrrev_i32_e32 v25, 31, v24
	v_lshlrev_b64 v[24:25], 11, v[24:25]
	v_lshl_add_u64 v[24:25], s[30:31], 0, v[24:25]
	v_lshl_add_u64 v[24:25], v[146:147], 1, v[24:25]
	v_cndmask_b32_e64 v17, v27, v29, s[4:5]
	v_cndmask_b32_e64 v16, v26, v28, s[4:5]
	v_lshl_add_u64 v[24:25], v[24:25], 0, v[136:137]
	global_store_dwordx4 v[24:25], v[16:19], off nt
	v_cndmask_b32_e64 v23, v23, v31, s[4:5]
	v_cndmask_b32_e64 v22, v22, v30, s[4:5]
	v_add_co_u32_e32 v16, vcc, s52, v24
	v_cndmask_b32_e64 v21, v21, v27, s[4:5]
	v_cndmask_b32_e64 v20, v20, v26, s[4:5]
	v_addc_co_u32_e32 v17, vcc, 0, v25, vcc
	s_addk_i32 s19, 0xb0
	global_store_dwordx4 v[16:17], v[20:23], off nt
	v_or_b32_e32 v16, s19, v150
	v_ashrrev_i32_e32 v17, 31, v16
	v_readlane_b32 s64, v239, 10
	v_lshlrev_b64 v[18:19], 12, v[16:17]
	v_readlane_b32 s65, v239, 11
	v_readlane_b32 s66, v239, 12
	v_readlane_b32 s67, v239, 13
	v_lshl_add_u64 v[18:19], s[64:65], 0, v[18:19]
	v_lshl_add_u64 v[30:31], v[146:147], 2, v[18:19]
	s_nop 0
	v_readlane_b32 s68, v239, 14
	v_readlane_b32 s69, v239, 15
	v_readlane_b32 s70, v239, 16
	v_readlane_b32 s71, v239, 17
	v_readlane_b32 s72, v239, 18
	v_readlane_b32 s73, v239, 19
	v_readlane_b32 s74, v239, 20
	v_readlane_b32 s75, v239, 21
	v_readlane_b32 s76, v239, 22
	v_readlane_b32 s77, v239, 23
	v_readlane_b32 s78, v239, 24
	v_readlane_b32 s79, v239, 25
	s_waitcnt vmcnt(12)
	v_mov_b64_e32 v[18:19], v[240:241]
	v_mov_b64_e32 v[20:21], v[242:243]
	v_mov_b64_e32 v[22:23], v[244:245]
	v_mov_b64_e32 v[24:25], v[246:247]
	v_mov_b64_e32 v[26:27], v[248:249]
	v_mov_b64_e32 v[28:29], v[250:251]
	v_mov_b64_e32 v[30:31], v[252:253]
	v_mov_b64_e32 v[32:33], v[254:255]
	v_pk_add_f32 v[14:15], v[14:15], v[20:21]
	v_pk_add_f32 v[12:13], v[12:13], v[18:19]
	v_pk_add_f32 v[10:11], v[10:11], v[24:25]
	v_pk_add_f32 v[8:9], v[8:9], v[22:23]
	v_pk_add_f32 v[6:7], v[6:7], v[28:29]
	v_pk_add_f32 v[4:5], v[4:5], v[26:27]
	v_pk_add_f32 v[2:3], v[2:3], v[32:33]
	v_pk_add_f32 v[0:1], v[0:1], v[30:31]
	v_mul_f32_e32 v18, v13, v13
	v_mul_f32_e32 v19, v15, v15
	v_mul_f32_e32 v20, v9, v9
	v_mul_f32_e32 v21, v11, v11
	v_mul_f32_e32 v22, v5, v5
	v_mul_f32_e32 v23, v7, v7
	v_mul_f32_e32 v24, v1, v1
	v_mul_f32_e32 v25, v3, v3
	v_fmac_f32_e32 v18, v12, v12
	v_fmac_f32_e32 v19, v14, v14
	v_fmac_f32_e32 v20, v8, v8
	v_fmac_f32_e32 v21, v10, v10
	v_fmac_f32_e32 v22, v4, v4
	v_fmac_f32_e32 v23, v6, v6
	v_fmac_f32_e32 v24, v0, v0
	v_fmac_f32_e32 v25, v2, v2
	v_add_f32_e32 v18, v18, v19
	v_add_f32_e32 v19, v20, v21
	v_add_f32_e32 v20, v22, v23
	v_add_f32_e32 v21, v24, v25
	v_add_f32_e32 v18, v18, v19
	v_add_f32_e32 v19, v20, v21
	v_add_f32_e32 v18, v18, v19
	ds_bpermute_b32 v19, v161, v18
	s_waitcnt lgkmcnt(0)
	v_add_f32_e32 v18, v18, v19
	ds_bpermute_b32 v19, v162, v18
	s_and_saveexec_b64 s[20:21], s[2:3]
	s_cbranch_execz .LBB0_604
	v_lshlrev_b64 v[16:17], 6, v[16:17]
	v_lshl_add_u64 v[16:17], s[82:83], 0, v[16:17]
	v_lshl_add_u64 v[16:17], s[0:1], 2, v[16:17]
	s_lshl_b32 s10, s55, 2
	v_lshl_add_u64 v[16:17], v[16:17], 0, s[10:11]
	s_waitcnt lgkmcnt(0)
	v_add_f32_e32 v18, v18, v19
	global_store_dword v[16:17], v18, off
